# v12: v11 + rope (EpiRetIn) epilogue: all sub-block cos/sin table loads hoisted to the epilogue top into free VGPRs, counted vmcnt
# speedup vs baseline: 1.0028x; 1.0001x over previous
; #define PG8_GAS __attribute__((address_space(1)))
;     __device__ __forceinline__ void store_rows(const f32x4& a0, const f32x4& a1, const f32x4& b0, const f32x4& b1, int type, bf16_t* base, size_t off) const {
;     ...
;         if (type == 1) { x0 = x0 * 0.0625f; x1 = x1 * 0.0625f; y0 = y0 * 0.0625f; y1 = y1 * 0.0625f; }
;     __device__ __forceinline__ void operator()(const f32x4 (&acc)[2][2][4][2], const Unit& u, int wr, int wc, int fr_in, int fq_in) const {
;     ...
;             for (int m = 0; m < 4; ++m) {
;                 const int pos = 16 * m + fr;
;                 const f32x4 c0 = *(const PG8_GAS f32x4*)(cosT + pos * 64 + fidx), c1 = *(const PG8_GAS f32x4*)(cosT + pos * 64 + fidx + 4), s0 = *(const PG8_GAS f32x4*)(sinT + pos * 64 + fidx), s1 = *(const PG8_GAS f32x4*)(sinT + pos * 64 + fidx + 4);
; #pragma unroll
;                 for (int ai = 0; ai < 2; ++ai) { const f32x4 a0 = acc[ai][0][m][0], a1 = acc[ai][0][m][1], b0 = acc[ai][1][m][0], b1 = acc[ai][1][m][1];
;                     store_rows(a0 * c0 - b0 * s0, a1 * c1 - b1 * s1, a0 * s0 + b0 * c0, a1 * s1 + b1 * c1, type, base, (size_t)(row0 + ai * HALF + m * 16) * 2048 + coff); }
.LBB0_686:
	s_and_b64 vcc, exec, s[6:7]
	s_cbranch_vccz .LBB0_723
	v_add_u32_e32 v132, s51, v153
	v_ashrrev_i32_e32 v133, 31, v132
	s_cmp_eq_u32 s23, 1
	s_cselect_b64 s[8:9], -1, 0
	v_lshlrev_b64 v[148:149], 1, v[148:149]
	s_mov_b64 s[6:7], -1
	s_andn2_b64 vcc, exec, s[18:19]
	v_lshlrev_b64 v[150:151], 2, v[132:133]
	s_cbranch_vccnz .LBB0_705
	v_lshlrev_b32_e32 v152, 6, v152
	v_ashrrev_i32_e32 v153, 31, v152
	v_lshlrev_b64 v[132:133], 2, v[152:153]
	v_lshl_add_u64 v[134:135], s[12:13], 0, v[132:133]
	v_lshl_add_u64 v[134:135], v[134:135], 0, v[150:151]
	v_lshl_add_u64 v[132:133], s[14:15], 0, v[132:133]
	global_load_dwordx4 v[140:143], v[134:135], off
	global_load_dwordx4 v[136:139], v[134:135], off offset:16
	v_lshl_add_u64 v[132:133], v[132:133], 0, v[150:151]
	global_load_dwordx4 v[144:147], v[132:133], off
	s_nop 0
	global_load_dwordx4 v[132:135], v[132:133], off offset:16
	v_add_u32_e32 v240, 0x400, v152
	v_ashrrev_i32_e32 v241, 31, v240
	v_lshlrev_b64 v[240:241], 2, v[240:241]
	v_lshl_add_u64 v[242:243], s[12:13], 0, v[240:241]
	v_lshl_add_u64 v[242:243], v[242:243], 0, v[150:151]
	v_lshl_add_u64 v[240:241], s[14:15], 0, v[240:241]
	v_lshl_add_u64 v[240:241], v[240:241], 0, v[150:151]
	global_load_dwordx4 v[200:203], v[242:243], off
	global_load_dwordx4 v[196:199], v[242:243], off offset:16
	global_load_dwordx4 v[204:207], v[240:241], off
	global_load_dwordx4 v[192:195], v[240:241], off offset:16
	v_add_u32_e32 v240, 0x800, v152
	v_ashrrev_i32_e32 v241, 31, v240
	v_lshlrev_b64 v[240:241], 2, v[240:241]
	v_lshl_add_u64 v[242:243], s[12:13], 0, v[240:241]
	v_lshl_add_u64 v[242:243], v[242:243], 0, v[150:151]
	v_lshl_add_u64 v[240:241], s[14:15], 0, v[240:241]
	v_lshl_add_u64 v[240:241], v[240:241], 0, v[150:151]
	global_load_dwordx4 v[216:219], v[242:243], off
	global_load_dwordx4 v[212:215], v[242:243], off offset:16
	global_load_dwordx4 v[220:223], v[240:241], off
	global_load_dwordx4 v[208:211], v[240:241], off offset:16
	v_add_u32_e32 v240, 0xc00, v152
	v_ashrrev_i32_e32 v241, 31, v240
	v_lshlrev_b64 v[240:241], 2, v[240:241]
	v_lshl_add_u64 v[242:243], s[12:13], 0, v[240:241]
	v_lshl_add_u64 v[242:243], v[242:243], 0, v[150:151]
	v_lshl_add_u64 v[240:241], s[14:15], 0, v[240:241]
	v_lshl_add_u64 v[240:241], v[240:241], 0, v[150:151]
	global_load_dwordx4 v[232:235], v[242:243], off
	global_load_dwordx4 v[228:231], v[242:243], off offset:16
	global_load_dwordx4 v[236:239], v[240:241], off
	global_load_dwordx4 v[224:227], v[240:241], off offset:16
	s_and_b64 vcc, exec, s[8:9]
	s_waitcnt vmcnt(15)
	v_pk_mul_f32 v[154:155], v[130:131], v[142:143]
	v_pk_mul_f32 v[156:157], v[128:129], v[140:141]
	s_waitcnt vmcnt(14)
	v_pk_mul_f32 v[158:159], v[126:127], v[138:139]
	v_pk_mul_f32 v[160:161], v[124:125], v[136:137]
	v_pk_mul_f32 v[178:179], v[122:123], v[142:143]
	v_pk_mul_f32 v[180:181], v[120:121], v[140:141]
	v_pk_mul_f32 v[188:189], v[118:119], v[138:139]
	v_pk_mul_f32 v[190:191], v[116:117], v[136:137]
	s_waitcnt vmcnt(13)
	v_pk_fma_f32 v[166:167], v[122:123], v[146:147], v[154:155] neg_lo:[0,0,1] neg_hi:[0,0,1]
	v_pk_fma_f32 v[168:169], v[120:121], v[144:145], v[156:157] neg_lo:[0,0,1] neg_hi:[0,0,1]
	s_waitcnt vmcnt(12)
	v_pk_fma_f32 v[162:163], v[118:119], v[134:135], v[158:159] neg_lo:[0,0,1] neg_hi:[0,0,1]
	v_pk_fma_f32 v[164:165], v[116:117], v[132:133], v[160:161] neg_lo:[0,0,1] neg_hi:[0,0,1]
	v_pk_fma_f32 v[158:159], v[130:131], v[146:147], v[178:179]
	v_pk_fma_f32 v[160:161], v[128:129], v[144:145], v[180:181]
	v_pk_fma_f32 v[154:155], v[126:127], v[134:135], v[188:189]
	v_pk_fma_f32 v[156:157], v[124:125], v[132:133], v[190:191]
	s_cbranch_vccz .LBB0_690
	v_pk_mul_f32 v[166:167], v[166:167], s[54:55] op_sel_hi:[1,0]
	v_pk_mul_f32 v[168:169], v[168:169], s[54:55] op_sel_hi:[1,0]
	v_pk_mul_f32 v[162:163], v[162:163], s[54:55] op_sel_hi:[1,0]
	v_pk_mul_f32 v[164:165], v[164:165], s[54:55] op_sel_hi:[1,0]
	v_pk_mul_f32 v[158:159], v[158:159], s[54:55] op_sel_hi:[1,0]
	v_pk_mul_f32 v[160:161], v[160:161], s[54:55] op_sel_hi:[1,0]
	v_pk_mul_f32 v[154:155], v[154:155], s[54:55] op_sel_hi:[1,0]
	v_pk_mul_f32 v[156:157], v[156:157], s[54:55] op_sel_hi:[1,0]

; #define PG8_GAS __attribute__((address_space(1)))
; __device__ __forceinline__ f32x4 silu4(f32x4 v) { return v * sigm4(v); }
; __device__ __forceinline__ u32x4 pack8(f32x4 v0, f32x4 v1) { u32x4 w; w.x = cvt_pk_bf16(v0[0], v0[1]); w.y = cvt_pk_bf16(v0[2], v0[3]); w.z = cvt_pk_bf16(v1[0], v1[1]); w.w = cvt_pk_bf16(v1[2], v1[3]); return w; }
;     __device__ __forceinline__ void store_rows(const f32x4& a0, const f32x4& a1, const f32x4& b0, const f32x4& b1, int type, bf16_t* base, size_t off) const {
;         f32x4 x0 = a0, x1 = a1, y0 = b0, y1 = b1;
;         if (type == 1) { x0 = x0 * 0.0625f; x1 = x1 * 0.0625f; y0 = y0 * 0.0625f; y1 = y1 * 0.0625f; }
;         if (type == 3) { x0 = silu4(x0); x1 = silu4(x1); y0 = silu4(y0); y1 = silu4(y1); }
;         st16(base, off, pack8(x0, x1));
;         st16(base, off + HALF, pack8(y0, y1));
;     __device__ __forceinline__ void operator()(const f32x4 (&acc)[2][2][4][2], const Unit& u, int wr, int wc, int fr_in, int fq_in) const {
;     ...
; #pragma unroll
;             for (int m = 0; m < 4; ++m) {
;                 const int pos = 16 * m + fr;
;                 const f32x4 c0 = *(const PG8_GAS f32x4*)(cosT + pos * 64 + fidx), c1 = *(const PG8_GAS f32x4*)(cosT + pos * 64 + fidx + 4), s0 = *(const PG8_GAS f32x4*)(sinT + pos * 64 + fidx), s1 = *(const PG8_GAS f32x4*)(sinT + pos * 64 + fidx + 4);
; #pragma unroll
;                 for (int ai = 0; ai < 2; ++ai) { const f32x4 a0 = acc[ai][0][m][0], a1 = acc[ai][0][m][1], b0 = acc[ai][1][m][0], b1 = acc[ai][1][m][1];
;                     store_rows(a0 * c0 - b0 * s0, a1 * c1 - b1 * s1, a0 * s0 + b0 * c0, a1 * s1 + b1 * c1, type, base, (size_t)(row0 + ai * HALF + m * 16) * 2048 + coff); }
;             }
.LBB0_692:
	v_add_u32_e32 v0, 0x80000, v3
	v_and_b32_e32 v0, -2, v0
	v_cvt_pk_bf16_f32 v136, v156, v157
	v_cvt_pk_bf16_f32 v137, v154, v155
	v_cvt_pk_bf16_f32 v138, v160, v161
	v_lshl_add_u64 v[144:145], s[30:31], 0, v[0:1]
	v_cvt_pk_bf16_f32 v139, v158, v159
	global_store_dwordx4 v[144:145], v[136:139], off
	v_add_u32_e32 v0, 0x80100, v3
	v_and_b32_e32 v0, -2, v0
	v_cvt_pk_bf16_f32 v136, v142, v143
	v_cvt_pk_bf16_f32 v137, v140, v141
	v_cvt_pk_bf16_f32 v138, v132, v133
	v_cvt_pk_bf16_f32 v139, v134, v135
	global_store_dwordx4 v0, v[136:139], s[30:31]
	s_and_b64 vcc, exec, s[6:7]
	s_waitcnt vmcnt(15)
	v_pk_mul_f32 v[154:155], v[114:115], v[202:203]
	v_pk_mul_f32 v[156:157], v[112:113], v[200:201]
	s_waitcnt vmcnt(14)
	v_pk_mul_f32 v[158:159], v[110:111], v[198:199]
	v_pk_mul_f32 v[160:161], v[108:109], v[196:197]
	v_pk_mul_f32 v[178:179], v[106:107], v[202:203]
	v_pk_mul_f32 v[180:181], v[104:105], v[200:201]
	v_pk_mul_f32 v[188:189], v[102:103], v[198:199]
	v_pk_mul_f32 v[190:191], v[100:101], v[196:197]
	s_waitcnt vmcnt(13)
	v_pk_fma_f32 v[166:167], v[106:107], v[206:207], v[154:155] neg_lo:[0,0,1] neg_hi:[0,0,1]
	v_pk_fma_f32 v[168:169], v[104:105], v[204:205], v[156:157] neg_lo:[0,0,1] neg_hi:[0,0,1]
	s_waitcnt vmcnt(12)
	v_pk_fma_f32 v[162:163], v[102:103], v[194:195], v[158:159] neg_lo:[0,0,1] neg_hi:[0,0,1]
	v_pk_fma_f32 v[164:165], v[100:101], v[192:193], v[160:161] neg_lo:[0,0,1] neg_hi:[0,0,1]
	v_pk_fma_f32 v[158:159], v[114:115], v[206:207], v[178:179]
	v_pk_fma_f32 v[160:161], v[112:113], v[204:205], v[180:181]
	v_pk_fma_f32 v[154:155], v[110:111], v[194:195], v[188:189]
	v_pk_fma_f32 v[156:157], v[108:109], v[192:193], v[190:191]
	s_cbranch_vccnz .LBB0_694
	v_pk_mul_f32 v[166:167], v[166:167], s[54:55] op_sel_hi:[1,0]
	v_pk_mul_f32 v[168:169], v[168:169], s[54:55] op_sel_hi:[1,0]
	v_pk_mul_f32 v[162:163], v[162:163], s[54:55] op_sel_hi:[1,0]
	v_pk_mul_f32 v[164:165], v[164:165], s[54:55] op_sel_hi:[1,0]
	v_pk_mul_f32 v[158:159], v[158:159], s[54:55] op_sel_hi:[1,0]
	v_pk_mul_f32 v[160:161], v[160:161], s[54:55] op_sel_hi:[1,0]
	v_pk_mul_f32 v[154:155], v[154:155], s[54:55] op_sel_hi:[1,0]
	v_pk_mul_f32 v[156:157], v[156:157], s[54:55] op_sel_hi:[1,0]
.LBB0_694:
	v_add_u32_e32 v0, 0x10000, v3
	v_and_b32_e32 v0, -2, v0
	v_cvt_pk_bf16_f32 v188, v168, v169
	v_cvt_pk_bf16_f32 v189, v166, v167
	v_cvt_pk_bf16_f32 v190, v164, v165
	v_cvt_pk_bf16_f32 v191, v162, v163
	v_lshl_add_u64 v[162:163], s[30:31], 0, v[0:1]
	v_add_u32_e32 v0, 0x10100, v3
	global_store_dwordx4 v[162:163], v[188:191], off
	v_cvt_pk_bf16_f32 v160, v160, v161
	v_cvt_pk_bf16_f32 v161, v158, v159
	v_cvt_pk_bf16_f32 v162, v156, v157
	v_cvt_pk_bf16_f32 v163, v154, v155
	v_and_b32_e32 v0, -2, v0
	global_store_dwordx4 v0, v[160:163], s[30:31]
	v_pk_mul_f32 v[154:155], v[50:51], v[202:203]
	v_pk_mul_f32 v[156:157], v[48:49], v[200:201]
	v_pk_mul_f32 v[158:159], v[46:47], v[198:199]
	v_pk_mul_f32 v[160:161], v[44:45], v[196:197]
	v_pk_mul_f32 v[142:143], v[42:43], v[202:203]
	v_pk_mul_f32 v[162:163], v[40:41], v[200:201]
	v_pk_mul_f32 v[138:139], v[38:39], v[198:199]
	v_pk_mul_f32 v[136:137], v[36:37], v[196:197]
	v_pk_fma_f32 v[154:155], v[42:43], v[206:207], v[154:155] neg_lo:[0,0,1] neg_hi:[0,0,1]
	v_pk_fma_f32 v[156:157], v[40:41], v[204:205], v[156:157] neg_lo:[0,0,1] neg_hi:[0,0,1]
	v_pk_fma_f32 v[158:159], v[38:39], v[194:195], v[158:159] neg_lo:[0,0,1] neg_hi:[0,0,1]
	v_pk_fma_f32 v[160:161], v[36:37], v[192:193], v[160:161] neg_lo:[0,0,1] neg_hi:[0,0,1]
	v_pk_fma_f32 v[140:141], v[50:51], v[206:207], v[142:143]
	v_pk_fma_f32 v[142:143], v[48:49], v[204:205], v[162:163]
	v_pk_fma_f32 v[134:135], v[46:47], v[194:195], v[138:139]
	s_and_b64 vcc, exec, s[6:7]
	v_pk_fma_f32 v[132:133], v[44:45], v[192:193], v[136:137]
	s_cbranch_vccnz .LBB0_696
	v_pk_mul_f32 v[154:155], v[154:155], s[54:55] op_sel_hi:[1,0]
	v_pk_mul_f32 v[156:157], v[156:157], s[54:55] op_sel_hi:[1,0]
	v_pk_mul_f32 v[158:159], v[158:159], s[54:55] op_sel_hi:[1,0]
	v_pk_mul_f32 v[160:161], v[160:161], s[54:55] op_sel_hi:[1,0]
	v_pk_mul_f32 v[140:141], v[140:141], s[54:55] op_sel_hi:[1,0]
	v_pk_mul_f32 v[142:143], v[142:143], s[54:55] op_sel_hi:[1,0]
	v_pk_mul_f32 v[134:135], v[134:135], s[54:55] op_sel_hi:[1,0]
	v_pk_mul_f32 v[132:133], v[132:133], s[54:55] op_sel_hi:[1,0]
.LBB0_696:
	v_add_u32_e32 v0, 0x90000, v3
	v_and_b32_e32 v0, -2, v0
	v_cvt_pk_bf16_f32 v136, v156, v157
	v_cvt_pk_bf16_f32 v137, v154, v155
	v_cvt_pk_bf16_f32 v138, v160, v161
	v_lshl_add_u64 v[144:145], s[30:31], 0, v[0:1]
	v_cvt_pk_bf16_f32 v139, v158, v159
	global_store_dwordx4 v[144:145], v[136:139], off
	v_add_u32_e32 v0, 0x90100, v3
	v_and_b32_e32 v0, -2, v0
	v_cvt_pk_bf16_f32 v136, v142, v143
	v_cvt_pk_bf16_f32 v137, v140, v141
	v_cvt_pk_bf16_f32 v138, v132, v133
	v_cvt_pk_bf16_f32 v139, v134, v135
	global_store_dwordx4 v0, v[136:139], s[30:31]
	s_and_b64 vcc, exec, s[6:7]
	s_waitcnt vmcnt(15)
	v_pk_mul_f32 v[154:155], v[98:99], v[218:219]
	v_pk_mul_f32 v[156:157], v[96:97], v[216:217]
	s_waitcnt vmcnt(14)
	v_pk_mul_f32 v[158:159], v[94:95], v[214:215]
	v_pk_mul_f32 v[160:161], v[92:93], v[212:213]
	v_pk_mul_f32 v[178:179], v[90:91], v[218:219]
	v_pk_mul_f32 v[180:181], v[88:89], v[216:217]
	v_pk_mul_f32 v[188:189], v[86:87], v[214:215]
	v_pk_mul_f32 v[190:191], v[84:85], v[212:213]
	s_waitcnt vmcnt(13)
	v_pk_fma_f32 v[166:167], v[90:91], v[222:223], v[154:155] neg_lo:[0,0,1] neg_hi:[0,0,1]
	v_pk_fma_f32 v[168:169], v[88:89], v[220:221], v[156:157] neg_lo:[0,0,1] neg_hi:[0,0,1]
	s_waitcnt vmcnt(12)
	v_pk_fma_f32 v[162:163], v[86:87], v[210:211], v[158:159] neg_lo:[0,0,1] neg_hi:[0,0,1]
	v_pk_fma_f32 v[164:165], v[84:85], v[208:209], v[160:161] neg_lo:[0,0,1] neg_hi:[0,0,1]
	v_pk_fma_f32 v[158:159], v[98:99], v[222:223], v[178:179]
	v_pk_fma_f32 v[160:161], v[96:97], v[220:221], v[180:181]
	v_pk_fma_f32 v[154:155], v[94:95], v[210:211], v[188:189]
	v_pk_fma_f32 v[156:157], v[92:93], v[208:209], v[190:191]
	s_cbranch_vccnz .LBB0_698
	v_pk_mul_f32 v[166:167], v[166:167], s[54:55] op_sel_hi:[1,0]
	v_pk_mul_f32 v[168:169], v[168:169], s[54:55] op_sel_hi:[1,0]
	v_pk_mul_f32 v[162:163], v[162:163], s[54:55] op_sel_hi:[1,0]
	v_pk_mul_f32 v[164:165], v[164:165], s[54:55] op_sel_hi:[1,0]
	v_pk_mul_f32 v[158:159], v[158:159], s[54:55] op_sel_hi:[1,0]
	v_pk_mul_f32 v[160:161], v[160:161], s[54:55] op_sel_hi:[1,0]
	v_pk_mul_f32 v[154:155], v[154:155], s[54:55] op_sel_hi:[1,0]
	v_pk_mul_f32 v[156:157], v[156:157], s[54:55] op_sel_hi:[1,0]
; #define PG8_GAS __attribute__((address_space(1)))
; __device__ __forceinline__ f32x4 silu4(f32x4 v) { return v * sigm4(v); }
; __device__ __forceinline__ u32x4 pack8(f32x4 v0, f32x4 v1) { u32x4 w; w.x = cvt_pk_bf16(v0[0], v0[1]); w.y = cvt_pk_bf16(v0[2], v0[3]); w.z = cvt_pk_bf16(v1[0], v1[1]); w.w = cvt_pk_bf16(v1[2], v1[3]); return w; }
;     __device__ __forceinline__ void store_rows(const f32x4& a0, const f32x4& a1, const f32x4& b0, const f32x4& b1, int type, bf16_t* base, size_t off) const {
;         f32x4 x0 = a0, x1 = a1, y0 = b0, y1 = b1;
;         if (type == 1) { x0 = x0 * 0.0625f; x1 = x1 * 0.0625f; y0 = y0 * 0.0625f; y1 = y1 * 0.0625f; }
;         if (type == 3) { x0 = silu4(x0); x1 = silu4(x1); y0 = silu4(y0); y1 = silu4(y1); }
;         st16(base, off, pack8(x0, x1));
;         st16(base, off + HALF, pack8(y0, y1));
;     __device__ __forceinline__ void operator()(const f32x4 (&acc)[2][2][4][2], const Unit& u, int wr, int wc, int fr_in, int fq_in) const {
;     ...
; #pragma unroll
;             for (int m = 0; m < 4; ++m) {
;                 const int pos = 16 * m + fr;
;                 const f32x4 c0 = *(const PG8_GAS f32x4*)(cosT + pos * 64 + fidx), c1 = *(const PG8_GAS f32x4*)(cosT + pos * 64 + fidx + 4), s0 = *(const PG8_GAS f32x4*)(sinT + pos * 64 + fidx), s1 = *(const PG8_GAS f32x4*)(sinT + pos * 64 + fidx + 4);
; #pragma unroll
;                 for (int ai = 0; ai < 2; ++ai) { const f32x4 a0 = acc[ai][0][m][0], a1 = acc[ai][0][m][1], b0 = acc[ai][1][m][0], b1 = acc[ai][1][m][1];
;                     store_rows(a0 * c0 - b0 * s0, a1 * c1 - b1 * s1, a0 * s0 + b0 * c0, a1 * s1 + b1 * c1, type, base, (size_t)(row0 + ai * HALF + m * 16) * 2048 + coff); }
;             }
.LBB0_698:
	v_add_u32_e32 v0, 0x20000, v3
	v_and_b32_e32 v0, -2, v0
	v_cvt_pk_bf16_f32 v188, v168, v169
	v_cvt_pk_bf16_f32 v189, v166, v167
	v_cvt_pk_bf16_f32 v190, v164, v165
	v_cvt_pk_bf16_f32 v191, v162, v163
	v_lshl_add_u64 v[162:163], s[30:31], 0, v[0:1]
	v_add_u32_e32 v0, 0x20100, v3
	global_store_dwordx4 v[162:163], v[188:191], off
	v_cvt_pk_bf16_f32 v160, v160, v161
	v_cvt_pk_bf16_f32 v161, v158, v159
	v_cvt_pk_bf16_f32 v162, v156, v157
	v_cvt_pk_bf16_f32 v163, v154, v155
	v_and_b32_e32 v0, -2, v0
	global_store_dwordx4 v0, v[160:163], s[30:31]
	v_pk_mul_f32 v[154:155], v[34:35], v[218:219]
	v_pk_mul_f32 v[156:157], v[32:33], v[216:217]
	v_pk_mul_f32 v[158:159], v[30:31], v[214:215]
	v_pk_mul_f32 v[160:161], v[28:29], v[212:213]
	v_pk_mul_f32 v[142:143], v[26:27], v[218:219]
	v_pk_mul_f32 v[162:163], v[24:25], v[216:217]
	v_pk_mul_f32 v[138:139], v[22:23], v[214:215]
	v_pk_mul_f32 v[136:137], v[20:21], v[212:213]
	v_pk_fma_f32 v[154:155], v[26:27], v[222:223], v[154:155] neg_lo:[0,0,1] neg_hi:[0,0,1]
	v_pk_fma_f32 v[156:157], v[24:25], v[220:221], v[156:157] neg_lo:[0,0,1] neg_hi:[0,0,1]
	v_pk_fma_f32 v[158:159], v[22:23], v[210:211], v[158:159] neg_lo:[0,0,1] neg_hi:[0,0,1]
	v_pk_fma_f32 v[160:161], v[20:21], v[208:209], v[160:161] neg_lo:[0,0,1] neg_hi:[0,0,1]
	v_pk_fma_f32 v[140:141], v[34:35], v[222:223], v[142:143]
	v_pk_fma_f32 v[142:143], v[32:33], v[220:221], v[162:163]
	v_pk_fma_f32 v[134:135], v[30:31], v[210:211], v[138:139]
	s_and_b64 vcc, exec, s[6:7]
	v_pk_fma_f32 v[132:133], v[28:29], v[208:209], v[136:137]
	s_cbranch_vccnz .LBB0_700
	v_pk_mul_f32 v[154:155], v[154:155], s[54:55] op_sel_hi:[1,0]
	v_pk_mul_f32 v[156:157], v[156:157], s[54:55] op_sel_hi:[1,0]
	v_pk_mul_f32 v[158:159], v[158:159], s[54:55] op_sel_hi:[1,0]
	v_pk_mul_f32 v[160:161], v[160:161], s[54:55] op_sel_hi:[1,0]
	v_pk_mul_f32 v[140:141], v[140:141], s[54:55] op_sel_hi:[1,0]
	v_pk_mul_f32 v[142:143], v[142:143], s[54:55] op_sel_hi:[1,0]
	v_pk_mul_f32 v[134:135], v[134:135], s[54:55] op_sel_hi:[1,0]
	v_pk_mul_f32 v[132:133], v[132:133], s[54:55] op_sel_hi:[1,0]
.LBB0_700:
	v_add_u32_e32 v0, 0xa0000, v3
	v_and_b32_e32 v0, -2, v0
	v_cvt_pk_bf16_f32 v136, v156, v157
	v_cvt_pk_bf16_f32 v137, v154, v155
	v_cvt_pk_bf16_f32 v138, v160, v161
	v_lshl_add_u64 v[144:145], s[30:31], 0, v[0:1]
	v_cvt_pk_bf16_f32 v139, v158, v159
	global_store_dwordx4 v[144:145], v[136:139], off
	v_add_u32_e32 v0, 0xa0100, v3
	v_and_b32_e32 v0, -2, v0
	v_cvt_pk_bf16_f32 v136, v142, v143
	v_cvt_pk_bf16_f32 v137, v140, v141
	v_cvt_pk_bf16_f32 v138, v132, v133
	v_cvt_pk_bf16_f32 v139, v134, v135
	global_store_dwordx4 v0, v[136:139], s[30:31]
	s_and_b64 vcc, exec, s[6:7]
	s_waitcnt vmcnt(15)
	v_pk_mul_f32 v[152:153], v[82:83], v[234:235]
	v_pk_mul_f32 v[154:155], v[80:81], v[232:233]
	s_waitcnt vmcnt(14)
	v_pk_mul_f32 v[156:157], v[78:79], v[230:231]
	v_pk_mul_f32 v[158:159], v[76:77], v[228:229]
	v_pk_mul_f32 v[168:169], v[74:75], v[234:235]
	v_pk_mul_f32 v[178:179], v[72:73], v[232:233]
	v_pk_mul_f32 v[180:181], v[70:71], v[230:231]
	v_pk_mul_f32 v[188:189], v[68:69], v[228:229]
	s_waitcnt vmcnt(13)
	v_pk_fma_f32 v[164:165], v[74:75], v[238:239], v[152:153] neg_lo:[0,0,1] neg_hi:[0,0,1]
	v_pk_fma_f32 v[166:167], v[72:73], v[236:237], v[154:155] neg_lo:[0,0,1] neg_hi:[0,0,1]
	s_waitcnt vmcnt(12)
	v_pk_fma_f32 v[160:161], v[70:71], v[226:227], v[156:157] neg_lo:[0,0,1] neg_hi:[0,0,1]
	v_pk_fma_f32 v[162:163], v[68:69], v[224:225], v[158:159] neg_lo:[0,0,1] neg_hi:[0,0,1]
	v_pk_fma_f32 v[156:157], v[82:83], v[238:239], v[168:169]
	v_pk_fma_f32 v[158:159], v[80:81], v[236:237], v[178:179]
	v_pk_fma_f32 v[152:153], v[78:79], v[226:227], v[180:181]
	v_pk_fma_f32 v[154:155], v[76:77], v[224:225], v[188:189]
	s_cbranch_vccnz .LBB0_702
	v_pk_mul_f32 v[164:165], v[164:165], s[54:55] op_sel_hi:[1,0]
	v_pk_mul_f32 v[166:167], v[166:167], s[54:55] op_sel_hi:[1,0]
	v_pk_mul_f32 v[160:161], v[160:161], s[54:55] op_sel_hi:[1,0]
	v_pk_mul_f32 v[162:163], v[162:163], s[54:55] op_sel_hi:[1,0]
	v_pk_mul_f32 v[156:157], v[156:157], s[54:55] op_sel_hi:[1,0]
	v_pk_mul_f32 v[158:159], v[158:159], s[54:55] op_sel_hi:[1,0]
	v_pk_mul_f32 v[152:153], v[152:153], s[54:55] op_sel_hi:[1,0]
	v_pk_mul_f32 v[154:155], v[154:155], s[54:55] op_sel_hi:[1,0]
.LBB0_702:
	v_add_u32_e32 v0, 0x30000, v3
	v_and_b32_e32 v0, -2, v0
	v_cvt_pk_bf16_f32 v166, v166, v167
	v_cvt_pk_bf16_f32 v167, v164, v165
	v_cvt_pk_bf16_f32 v168, v162, v163
	v_cvt_pk_bf16_f32 v169, v160, v161
	v_lshl_add_u64 v[160:161], s[30:31], 0, v[0:1]
	v_add_u32_e32 v0, 0x30100, v3
	global_store_dwordx4 v[160:161], v[166:169], off
	v_cvt_pk_bf16_f32 v158, v158, v159
	v_cvt_pk_bf16_f32 v159, v156, v157
	v_cvt_pk_bf16_f32 v160, v154, v155
	v_cvt_pk_bf16_f32 v161, v152, v153
	v_and_b32_e32 v0, -2, v0
	global_store_dwordx4 v0, v[158:161], s[30:31]
	v_pk_mul_f32 v[152:153], v[18:19], v[234:235]
	v_pk_mul_f32 v[154:155], v[16:17], v[232:233]
	v_pk_mul_f32 v[156:157], v[14:15], v[230:231]
	v_pk_mul_f32 v[158:159], v[12:13], v[228:229]
	v_pk_mul_f32 v[142:143], v[10:11], v[234:235]
	v_pk_mul_f32 v[160:161], v[8:9], v[232:233]
	v_pk_mul_f32 v[138:139], v[6:7], v[230:231]
	v_pk_mul_f32 v[136:137], v[4:5], v[228:229]
	v_pk_fma_f32 v[152:153], v[10:11], v[238:239], v[152:153] neg_lo:[0,0,1] neg_hi:[0,0,1]
	v_pk_fma_f32 v[154:155], v[8:9], v[236:237], v[154:155] neg_lo:[0,0,1] neg_hi:[0,0,1]
	v_pk_fma_f32 v[156:157], v[6:7], v[226:227], v[156:157] neg_lo:[0,0,1] neg_hi:[0,0,1]
	v_pk_fma_f32 v[158:159], v[4:5], v[224:225], v[158:159] neg_lo:[0,0,1] neg_hi:[0,0,1]
	v_pk_fma_f32 v[140:141], v[18:19], v[238:239], v[142:143]
	v_pk_fma_f32 v[142:143], v[16:17], v[236:237], v[160:161]
	v_pk_fma_f32 v[138:139], v[14:15], v[226:227], v[138:139]
	s_and_b64 vcc, exec, s[6:7]
	v_pk_fma_f32 v[134:135], v[12:13], v[224:225], v[136:137]
	s_cbranch_vccnz .LBB0_704
	v_pk_mul_f32 v[152:153], v[152:153], s[54:55] op_sel_hi:[1,0]
	v_pk_mul_f32 v[154:155], v[154:155], s[54:55] op_sel_hi:[1,0]
	v_pk_mul_f32 v[156:157], v[156:157], s[54:55] op_sel_hi:[1,0]
	v_pk_mul_f32 v[158:159], v[158:159], s[54:55] op_sel_hi:[1,0]
	v_pk_mul_f32 v[140:141], v[140:141], s[54:55] op_sel_hi:[1,0]
	v_pk_mul_f32 v[142:143], v[142:143], s[54:55] op_sel_hi:[1,0]
	v_pk_mul_f32 v[138:139], v[138:139], s[54:55] op_sel_hi:[1,0]
	v_pk_mul_f32 v[134:135], v[134:135], s[54:55] op_sel_hi:[1,0]

; #define PG8_GAS __attribute__((address_space(1)))
; __device__ __forceinline__ f32x4 silu4(f32x4 v) { return v * sigm4(v); }
; __device__ __forceinline__ u32x4 pack8(f32x4 v0, f32x4 v1) { u32x4 w; w.x = cvt_pk_bf16(v0[0], v0[1]); w.y = cvt_pk_bf16(v0[2], v0[3]); w.z = cvt_pk_bf16(v1[0], v1[1]); w.w = cvt_pk_bf16(v1[2], v1[3]); return w; }
;     __device__ __forceinline__ void store_rows(const f32x4& a0, const f32x4& a1, const f32x4& b0, const f32x4& b1, int type, bf16_t* base, size_t off) const {
;         f32x4 x0 = a0, x1 = a1, y0 = b0, y1 = b1;
;         if (type == 1) { x0 = x0 * 0.0625f; x1 = x1 * 0.0625f; y0 = y0 * 0.0625f; y1 = y1 * 0.0625f; }
;         if (type == 3) { x0 = silu4(x0); x1 = silu4(x1); y0 = silu4(y0); y1 = silu4(y1); }
;         st16(base, off, pack8(x0, x1));
;         st16(base, off + HALF, pack8(y0, y1));
;     __device__ __forceinline__ void operator()(const f32x4 (&acc)[2][2][4][2], const Unit& u, int wr, int wc, int fr_in, int fq_in) const {
;     ...
;         } else if (wc < 2) {
; #pragma unroll
;             for (int ai = 0; ai < 2; ++ai) {
;                 const int pos = (4 * u.pm + 2 * ai + wr) & 63;
;                 const f32x4 c0 = *(const PG8_GAS f32x4*)(cosT + pos * 64 + fidx), c1 = *(const PG8_GAS f32x4*)(cosT + pos * 64 + fidx + 4), s0 = *(const PG8_GAS f32x4*)(sinT + pos * 64 + fidx), s1 = *(const PG8_GAS f32x4*)(sinT + pos * 64 + fidx + 4);
; #pragma unroll
;                 for (int m = 0; m < 4; ++m) { const f32x4 a0 = acc[ai][0][m][0], a1 = acc[ai][0][m][1], b0 = acc[ai][1][m][0], b1 = acc[ai][1][m][1];
;                     store_rows(a0 * c0 - b0 * s0, a1 * c1 - b1 * s1, a0 * s0 + b0 * c0, a1 * s1 + b1 * c1, type, base, (size_t)(row0 + ai * HALF + m * 16) * 2048 + coff); }
;             }
.LBB0_705:
	s_and_b64 vcc, exec, s[6:7]
	s_cbranch_vccz .LBB0_723
	s_and_b32 s6, s21, 0xfc0
	s_lshl_b32 s23, s6, 2
	s_add_u32 s6, s14, s23
	s_addc_u32 s7, s15, 0
	v_lshl_add_u64 v[136:137], s[6:7], 0, v[150:151]
	s_add_u32 s6, s12, s23
	s_addc_u32 s7, s13, 0
	v_lshl_add_u64 v[144:145], s[6:7], 0, v[150:151]
	global_load_dwordx4 v[132:135], v[136:137], off offset:16
	s_nop 0
	global_load_dwordx4 v[136:139], v[136:137], off
	s_nop 0
	global_load_dwordx4 v[140:143], v[144:145], off offset:16
	s_nop 0
	global_load_dwordx4 v[144:147], v[144:145], off
	s_add_i32 s6, s21, 0x80
	s_and_b32 s6, s6, 0xfc0
	s_lshl_b32 s6, s6, 2
	v_mov_b32_e32 v240, s6
	v_mov_b32_e32 v241, 0
	v_lshl_add_u64 v[242:243], s[14:15], 0, v[240:241]
	v_lshl_add_u64 v[242:243], v[242:243], 0, v[150:151]
	v_lshl_add_u64 v[240:241], s[12:13], 0, v[240:241]
	v_lshl_add_u64 v[240:241], v[240:241], 0, v[150:151]
	global_load_dwordx4 v[192:195], v[242:243], off offset:16
	global_load_dwordx4 v[196:199], v[242:243], off
	global_load_dwordx4 v[200:203], v[240:241], off offset:16
	global_load_dwordx4 v[204:207], v[240:241], off
	v_cndmask_b32_e64 v0, 0, 1, s[8:9]
	v_cmp_ne_u32_e64 s[6:7], 1, v0
	s_andn2_b64 vcc, exec, s[8:9]
	s_waitcnt vmcnt(4)
	v_pk_mul_f32 v[152:153], v[130:131], v[146:147]
	v_pk_mul_f32 v[156:157], v[128:129], v[144:145]
	v_pk_fma_f32 v[154:155], v[122:123], v[138:139], v[152:153] neg_lo:[0,0,1] neg_hi:[0,0,1]
	v_pk_mul_f32 v[152:153], v[126:127], v[142:143]
	v_pk_mul_f32 v[122:123], v[122:123], v[146:147]
	v_pk_mul_f32 v[160:161], v[120:121], v[144:145]
	v_pk_fma_f32 v[158:159], v[120:121], v[136:137], v[156:157] neg_lo:[0,0,1] neg_hi:[0,0,1]
	v_pk_mul_f32 v[156:157], v[124:125], v[140:141]
	v_pk_fma_f32 v[152:153], v[118:119], v[134:135], v[152:153] neg_lo:[0,0,1] neg_hi:[0,0,1]
	v_pk_fma_f32 v[120:121], v[130:131], v[138:139], v[122:123]
	v_pk_fma_f32 v[122:123], v[128:129], v[136:137], v[160:161]
	v_pk_mul_f32 v[118:119], v[118:119], v[142:143]
	v_pk_mul_f32 v[128:129], v[116:117], v[140:141]
	v_pk_fma_f32 v[156:157], v[116:117], v[132:133], v[156:157] neg_lo:[0,0,1] neg_hi:[0,0,1]
	v_pk_fma_f32 v[116:117], v[126:127], v[134:135], v[118:119]
	v_pk_fma_f32 v[118:119], v[124:125], v[132:133], v[128:129]
	s_cbranch_vccnz .LBB0_708
	v_pk_mul_f32 v[154:155], v[154:155], s[54:55] op_sel_hi:[1,0]
	v_pk_mul_f32 v[158:159], v[158:159], s[54:55] op_sel_hi:[1,0]
	v_pk_mul_f32 v[152:153], v[152:153], s[54:55] op_sel_hi:[1,0]
	v_pk_mul_f32 v[156:157], v[156:157], s[54:55] op_sel_hi:[1,0]
	v_pk_mul_f32 v[120:121], v[120:121], s[54:55] op_sel_hi:[1,0]
	v_pk_mul_f32 v[122:123], v[122:123], s[54:55] op_sel_hi:[1,0]
	v_pk_mul_f32 v[116:117], v[116:117], s[54:55] op_sel_hi:[1,0]
	v_pk_mul_f32 v[118:119], v[118:119], s[54:55] op_sel_hi:[1,0]

; #define PG8_GAS __attribute__((address_space(1)))
; __device__ __forceinline__ f32x4 silu4(f32x4 v) { return v * sigm4(v); }
; __device__ __forceinline__ u32x4 pack8(f32x4 v0, f32x4 v1) { u32x4 w; w.x = cvt_pk_bf16(v0[0], v0[1]); w.y = cvt_pk_bf16(v0[2], v0[3]); w.z = cvt_pk_bf16(v1[0], v1[1]); w.w = cvt_pk_bf16(v1[2], v1[3]); return w; }
;     __device__ __forceinline__ void store_rows(const f32x4& a0, const f32x4& a1, const f32x4& b0, const f32x4& b1, int type, bf16_t* base, size_t off) const {
;         f32x4 x0 = a0, x1 = a1, y0 = b0, y1 = b1;
;         if (type == 1) { x0 = x0 * 0.0625f; x1 = x1 * 0.0625f; y0 = y0 * 0.0625f; y1 = y1 * 0.0625f; }
;         if (type == 3) { x0 = silu4(x0); x1 = silu4(x1); y0 = silu4(y0); y1 = silu4(y1); }
;         st16(base, off, pack8(x0, x1));
;         st16(base, off + HALF, pack8(y0, y1));
;     __device__ __forceinline__ void operator()(const f32x4 (&acc)[2][2][4][2], const Unit& u, int wr, int wc, int fr_in, int fq_in) const {
;     ...
;         } else if (wc < 2) {
; #pragma unroll
;             for (int ai = 0; ai < 2; ++ai) {
;                 const int pos = (4 * u.pm + 2 * ai + wr) & 63;
;                 const f32x4 c0 = *(const PG8_GAS f32x4*)(cosT + pos * 64 + fidx), c1 = *(const PG8_GAS f32x4*)(cosT + pos * 64 + fidx + 4), s0 = *(const PG8_GAS f32x4*)(sinT + pos * 64 + fidx), s1 = *(const PG8_GAS f32x4*)(sinT + pos * 64 + fidx + 4);
; #pragma unroll
;                 for (int m = 0; m < 4; ++m) { const f32x4 a0 = acc[ai][0][m][0], a1 = acc[ai][0][m][1], b0 = acc[ai][1][m][0], b1 = acc[ai][1][m][1];
;                     store_rows(a0 * c0 - b0 * s0, a1 * c1 - b1 * s1, a0 * s0 + b0 * c0, a1 * s1 + b1 * c1, type, base, (size_t)(row0 + ai * HALF + m * 16) * 2048 + coff); }
;             }
.LBB0_714:
	s_addk_i32 s21, 0x80
	s_and_b32 s8, s21, 0xfc0
	v_add_u32_e32 v0, 0x30000, v3
	s_lshl_b32 s21, s8, 2
	v_and_b32_e32 v0, -2, v0
	s_add_u32 s8, s14, s21
	v_lshl_add_u64 v[80:81], s[30:31], 0, v[0:1]
	s_addc_u32 s9, s15, 0
	v_cvt_pk_bf16_f32 v76, v86, v87
	v_cvt_pk_bf16_f32 v77, v84, v85
	v_cvt_pk_bf16_f32 v78, v90, v91
	v_cvt_pk_bf16_f32 v79, v88, v89
	global_store_dwordx4 v[80:81], v[76:79], off
	v_cvt_pk_bf16_f32 v74, v74, v75
	v_cvt_pk_bf16_f32 v75, v72, v73
	v_add_u32_e32 v0, 0x30100, v3
	s_add_u32 s8, s12, s21
	v_and_b32_e32 v0, -2, v0
	s_addc_u32 s9, s13, 0
	v_cvt_pk_bf16_f32 v76, v70, v71
	v_cvt_pk_bf16_f32 v77, v68, v69
	global_store_dwordx4 v0, v[74:77], s[30:31]
	s_and_b64 vcc, exec, s[6:7]
	s_waitcnt vmcnt(8)
	v_pk_mul_f32 v[84:85], v[66:67], v[206:207]
	v_pk_mul_f32 v[88:89], v[64:65], v[204:205]
	v_pk_fma_f32 v[86:87], v[58:59], v[198:199], v[84:85] neg_lo:[0,0,1] neg_hi:[0,0,1]
	v_pk_mul_f32 v[84:85], v[62:63], v[202:203]
	v_pk_mul_f32 v[58:59], v[58:59], v[206:207]
	v_pk_mul_f32 v[92:93], v[56:57], v[204:205]
	v_pk_fma_f32 v[90:91], v[56:57], v[196:197], v[88:89] neg_lo:[0,0,1] neg_hi:[0,0,1]
	v_pk_mul_f32 v[88:89], v[60:61], v[200:201]
	v_pk_fma_f32 v[84:85], v[54:55], v[194:195], v[84:85] neg_lo:[0,0,1] neg_hi:[0,0,1]
	v_pk_fma_f32 v[56:57], v[66:67], v[198:199], v[58:59]
	v_pk_fma_f32 v[58:59], v[64:65], v[196:197], v[92:93]
	v_pk_mul_f32 v[54:55], v[54:55], v[202:203]
	v_pk_mul_f32 v[64:65], v[52:53], v[200:201]
	v_pk_fma_f32 v[88:89], v[52:53], v[192:193], v[88:89] neg_lo:[0,0,1] neg_hi:[0,0,1]
	v_pk_fma_f32 v[52:53], v[62:63], v[194:195], v[54:55]
	v_pk_fma_f32 v[54:55], v[60:61], v[192:193], v[64:65]
	s_cbranch_vccnz .LBB0_716
	v_pk_mul_f32 v[86:87], v[86:87], s[54:55] op_sel_hi:[1,0]
	v_pk_mul_f32 v[90:91], v[90:91], s[54:55] op_sel_hi:[1,0]
	v_pk_mul_f32 v[84:85], v[84:85], s[54:55] op_sel_hi:[1,0]
	v_pk_mul_f32 v[88:89], v[88:89], s[54:55] op_sel_hi:[1,0]
	v_pk_mul_f32 v[56:57], v[56:57], s[54:55] op_sel_hi:[1,0]
	v_pk_mul_f32 v[58:59], v[58:59], s[54:55] op_sel_hi:[1,0]
	v_pk_mul_f32 v[52:53], v[52:53], s[54:55] op_sel_hi:[1,0]
	v_pk_mul_f32 v[54:55], v[54:55], s[54:55] op_sel_hi:[1,0]
.LBB0_716:
	v_add_u32_e32 v0, 0x80000, v3
	v_and_b32_e32 v0, -2, v0
	v_cvt_pk_bf16_f32 v60, v90, v91
	v_cvt_pk_bf16_f32 v61, v86, v87
	v_lshl_add_u64 v[64:65], s[30:31], 0, v[0:1]
	v_add_u32_e32 v0, 0x80100, v3
	v_cvt_pk_bf16_f32 v62, v88, v89
	v_cvt_pk_bf16_f32 v63, v84, v85
	global_store_dwordx4 v[64:65], v[60:63], off
	v_cvt_pk_bf16_f32 v58, v58, v59
	v_cvt_pk_bf16_f32 v59, v56, v57
	v_and_b32_e32 v0, -2, v0
	v_pk_mul_f32 v[56:57], v[46:47], v[202:203]
	v_cvt_pk_bf16_f32 v60, v54, v55
	v_cvt_pk_bf16_f32 v61, v52, v53
	v_pk_mul_f32 v[52:53], v[50:51], v[206:207]
	global_store_dwordx4 v0, v[58:61], s[30:31]
	v_pk_mul_f32 v[54:55], v[48:49], v[204:205]
	v_pk_fma_f32 v[52:53], v[42:43], v[198:199], v[52:53] neg_lo:[0,0,1] neg_hi:[0,0,1]
	v_pk_mul_f32 v[42:43], v[42:43], v[206:207]
	v_pk_mul_f32 v[60:61], v[40:41], v[204:205]
	v_pk_fma_f32 v[54:55], v[40:41], v[196:197], v[54:55] neg_lo:[0,0,1] neg_hi:[0,0,1]
	v_pk_mul_f32 v[58:59], v[44:45], v[200:201]
	v_pk_fma_f32 v[56:57], v[38:39], v[194:195], v[56:57] neg_lo:[0,0,1] neg_hi:[0,0,1]
	v_pk_fma_f32 v[40:41], v[50:51], v[198:199], v[42:43]
	v_pk_fma_f32 v[42:43], v[48:49], v[196:197], v[60:61]
	v_pk_mul_f32 v[38:39], v[38:39], v[202:203]
	v_pk_mul_f32 v[48:49], v[36:37], v[200:201]
	v_pk_fma_f32 v[58:59], v[36:37], v[192:193], v[58:59] neg_lo:[0,0,1] neg_hi:[0,0,1]
	v_pk_fma_f32 v[36:37], v[46:47], v[194:195], v[38:39]
	s_and_b64 vcc, exec, s[6:7]
	v_pk_fma_f32 v[38:39], v[44:45], v[192:193], v[48:49]
	s_cbranch_vccnz .LBB0_718
	v_pk_mul_f32 v[52:53], v[52:53], s[54:55] op_sel_hi:[1,0]
	v_pk_mul_f32 v[54:55], v[54:55], s[54:55] op_sel_hi:[1,0]
	v_pk_mul_f32 v[56:57], v[56:57], s[54:55] op_sel_hi:[1,0]
	v_pk_mul_f32 v[58:59], v[58:59], s[54:55] op_sel_hi:[1,0]
	v_pk_mul_f32 v[40:41], v[40:41], s[54:55] op_sel_hi:[1,0]
	v_pk_mul_f32 v[42:43], v[42:43], s[54:55] op_sel_hi:[1,0]
	v_pk_mul_f32 v[36:37], v[36:37], s[54:55] op_sel_hi:[1,0]
	v_pk_mul_f32 v[38:39], v[38:39], s[54:55] op_sel_hi:[1,0]
; #define PG8_GAS __attribute__((address_space(1)))
; __device__ __forceinline__ f32x4 silu4(f32x4 v) { return v * sigm4(v); }
; __device__ __forceinline__ u32x4 pack8(f32x4 v0, f32x4 v1) { u32x4 w; w.x = cvt_pk_bf16(v0[0], v0[1]); w.y = cvt_pk_bf16(v0[2], v0[3]); w.z = cvt_pk_bf16(v1[0], v1[1]); w.w = cvt_pk_bf16(v1[2], v1[3]); return w; }
;     __device__ __forceinline__ void store_rows(const f32x4& a0, const f32x4& a1, const f32x4& b0, const f32x4& b1, int type, bf16_t* base, size_t off) const {
;         f32x4 x0 = a0, x1 = a1, y0 = b0, y1 = b1;
;         if (type == 1) { x0 = x0 * 0.0625f; x1 = x1 * 0.0625f; y0 = y0 * 0.0625f; y1 = y1 * 0.0625f; }
;         if (type == 3) { x0 = silu4(x0); x1 = silu4(x1); y0 = silu4(y0); y1 = silu4(y1); }
;         st16(base, off, pack8(x0, x1));
;         st16(base, off + HALF, pack8(y0, y1));
;     __device__ __forceinline__ void operator()(const f32x4 (&acc)[2][2][4][2], const Unit& u, int wr, int wc, int fr_in, int fq_in) const {
;     ...
;         } else if (wc < 2) {
; #pragma unroll
;             for (int ai = 0; ai < 2; ++ai) {
;                 const int pos = (4 * u.pm + 2 * ai + wr) & 63;
;                 const f32x4 c0 = *(const PG8_GAS f32x4*)(cosT + pos * 64 + fidx), c1 = *(const PG8_GAS f32x4*)(cosT + pos * 64 + fidx + 4), s0 = *(const PG8_GAS f32x4*)(sinT + pos * 64 + fidx), s1 = *(const PG8_GAS f32x4*)(sinT + pos * 64 + fidx + 4);
; #pragma unroll
;                 for (int m = 0; m < 4; ++m) { const f32x4 a0 = acc[ai][0][m][0], a1 = acc[ai][0][m][1], b0 = acc[ai][1][m][0], b1 = acc[ai][1][m][1];
;                     store_rows(a0 * c0 - b0 * s0, a1 * c1 - b1 * s1, a0 * s0 + b0 * c0, a1 * s1 + b1 * c1, type, base, (size_t)(row0 + ai * HALF + m * 16) * 2048 + coff); }
;             }
.LBB0_718:
	v_add_u32_e32 v0, 0x90000, v3
	v_and_b32_e32 v0, -2, v0
	v_cvt_pk_bf16_f32 v44, v54, v55
	v_cvt_pk_bf16_f32 v45, v52, v53
	v_lshl_add_u64 v[48:49], s[30:31], 0, v[0:1]
	v_add_u32_e32 v0, 0x90100, v3
	v_cvt_pk_bf16_f32 v46, v58, v59
	v_cvt_pk_bf16_f32 v47, v56, v57
	global_store_dwordx4 v[48:49], v[44:47], off
	v_cvt_pk_bf16_f32 v42, v42, v43
	v_cvt_pk_bf16_f32 v43, v40, v41
	v_and_b32_e32 v0, -2, v0
	v_pk_mul_f32 v[40:41], v[30:31], v[202:203]
	v_cvt_pk_bf16_f32 v44, v38, v39
	v_cvt_pk_bf16_f32 v45, v36, v37
	v_pk_mul_f32 v[36:37], v[34:35], v[206:207]
	global_store_dwordx4 v0, v[42:45], s[30:31]
	v_pk_mul_f32 v[38:39], v[32:33], v[204:205]
	v_pk_fma_f32 v[36:37], v[26:27], v[198:199], v[36:37] neg_lo:[0,0,1] neg_hi:[0,0,1]
	v_pk_mul_f32 v[26:27], v[26:27], v[206:207]
	v_pk_mul_f32 v[44:45], v[24:25], v[204:205]
	v_pk_fma_f32 v[38:39], v[24:25], v[196:197], v[38:39] neg_lo:[0,0,1] neg_hi:[0,0,1]
	v_pk_mul_f32 v[42:43], v[28:29], v[200:201]
	v_pk_fma_f32 v[40:41], v[22:23], v[194:195], v[40:41] neg_lo:[0,0,1] neg_hi:[0,0,1]
	v_pk_fma_f32 v[24:25], v[34:35], v[198:199], v[26:27]
	v_pk_fma_f32 v[26:27], v[32:33], v[196:197], v[44:45]
	v_pk_mul_f32 v[22:23], v[22:23], v[202:203]
	v_pk_mul_f32 v[32:33], v[20:21], v[200:201]
	v_pk_fma_f32 v[42:43], v[20:21], v[192:193], v[42:43] neg_lo:[0,0,1] neg_hi:[0,0,1]
	v_pk_fma_f32 v[20:21], v[30:31], v[194:195], v[22:23]
	s_and_b64 vcc, exec, s[6:7]
	v_pk_fma_f32 v[22:23], v[28:29], v[192:193], v[32:33]
	s_cbranch_vccnz .LBB0_720
	v_pk_mul_f32 v[36:37], v[36:37], s[54:55] op_sel_hi:[1,0]
	v_pk_mul_f32 v[38:39], v[38:39], s[54:55] op_sel_hi:[1,0]
	v_pk_mul_f32 v[40:41], v[40:41], s[54:55] op_sel_hi:[1,0]
	v_pk_mul_f32 v[42:43], v[42:43], s[54:55] op_sel_hi:[1,0]
	v_pk_mul_f32 v[24:25], v[24:25], s[54:55] op_sel_hi:[1,0]
	v_pk_mul_f32 v[26:27], v[26:27], s[54:55] op_sel_hi:[1,0]
	v_pk_mul_f32 v[20:21], v[20:21], s[54:55] op_sel_hi:[1,0]
	v_pk_mul_f32 v[22:23], v[22:23], s[54:55] op_sel_hi:[1,0]
.LBB0_720:
	v_add_u32_e32 v0, 0xa0000, v3
	v_and_b32_e32 v0, -2, v0
	v_cvt_pk_bf16_f32 v28, v38, v39
	v_cvt_pk_bf16_f32 v29, v36, v37
	v_lshl_add_u64 v[32:33], s[30:31], 0, v[0:1]
	v_add_u32_e32 v0, 0xa0100, v3
	v_cvt_pk_bf16_f32 v30, v42, v43
	v_cvt_pk_bf16_f32 v31, v40, v41
	global_store_dwordx4 v[32:33], v[28:31], off
	v_cvt_pk_bf16_f32 v26, v26, v27
	v_cvt_pk_bf16_f32 v27, v24, v25
	v_and_b32_e32 v0, -2, v0
	v_pk_mul_f32 v[24:25], v[14:15], v[202:203]
	v_cvt_pk_bf16_f32 v28, v22, v23
	v_cvt_pk_bf16_f32 v29, v20, v21
	v_pk_mul_f32 v[20:21], v[18:19], v[206:207]
	global_store_dwordx4 v0, v[26:29], s[30:31]
	v_pk_mul_f32 v[22:23], v[16:17], v[204:205]
	v_pk_fma_f32 v[20:21], v[10:11], v[198:199], v[20:21] neg_lo:[0,0,1] neg_hi:[0,0,1]
	v_pk_mul_f32 v[10:11], v[10:11], v[206:207]
	v_pk_mul_f32 v[28:29], v[8:9], v[204:205]
	v_pk_fma_f32 v[22:23], v[8:9], v[196:197], v[22:23] neg_lo:[0,0,1] neg_hi:[0,0,1]
	v_pk_mul_f32 v[26:27], v[12:13], v[200:201]
	v_pk_fma_f32 v[24:25], v[6:7], v[194:195], v[24:25] neg_lo:[0,0,1] neg_hi:[0,0,1]
	v_pk_fma_f32 v[8:9], v[18:19], v[198:199], v[10:11]
	v_pk_fma_f32 v[10:11], v[16:17], v[196:197], v[28:29]
	v_pk_mul_f32 v[6:7], v[6:7], v[202:203]
	v_pk_mul_f32 v[16:17], v[4:5], v[200:201]
	v_pk_fma_f32 v[26:27], v[4:5], v[192:193], v[26:27] neg_lo:[0,0,1] neg_hi:[0,0,1]
	v_pk_fma_f32 v[4:5], v[14:15], v[194:195], v[6:7]
	s_and_b64 vcc, exec, s[6:7]
	v_pk_fma_f32 v[6:7], v[12:13], v[192:193], v[16:17]
	s_cbranch_vccnz .LBB0_722
	v_pk_mul_f32 v[20:21], v[20:21], s[54:55] op_sel_hi:[1,0]
	v_pk_mul_f32 v[22:23], v[22:23], s[54:55] op_sel_hi:[1,0]
	v_pk_mul_f32 v[24:25], v[24:25], s[54:55] op_sel_hi:[1,0]
	v_pk_mul_f32 v[26:27], v[26:27], s[54:55] op_sel_hi:[1,0]
	v_pk_mul_f32 v[8:9], v[8:9], s[54:55] op_sel_hi:[1,0]
	v_pk_mul_f32 v[10:11], v[10:11], s[54:55] op_sel_hi:[1,0]
	v_pk_mul_f32 v[4:5], v[4:5], s[54:55] op_sel_hi:[1,0]
	v_pk_mul_f32 v[6:7], v[6:7], s[54:55] op_sel_hi:[1,0]
